# v039 + V-ring base address adds moved into the mandatory MFMA->VALU wait slot after the QK MFMAs (s_nop 10 -> 4 VALU + s_nop 6) in both MLA loops
# speedup vs baseline: 1.0004x; 1.0004x over previous
.LBB0_566:
	s_and_saveexec_b64 s[22:23], vcc
	s_cbranch_execz .LBB0_555
	s_waitcnt lgkmcnt(7)
	v_mfma_f32_32x32x16_bf16 v[96:111], v[196:199], v[148:151], 0
	ds_read_b128 v[196:199], v188 offset:256
	s_waitcnt lgkmcnt(7)
	v_mfma_f32_32x32x16_bf16 v[96:111], v[202:205], v[144:147], v[96:111]
	ds_read_b128 v[202:205], v188 offset:288
	s_waitcnt lgkmcnt(7)
	v_mfma_f32_32x32x16_bf16 v[96:111], v[206:209], v[140:143], v[96:111]
	ds_read_b128 v[206:209], v188 offset:10752
	s_waitcnt lgkmcnt(7)
	v_mfma_f32_32x32x16_bf16 v[96:111], v[210:213], v[136:139], v[96:111]
	ds_read_b128 v[210:213], v188 offset:10784
	s_waitcnt lgkmcnt(7)
	v_mfma_f32_32x32x16_bf16 v[96:111], v[220:223], v[132:135], v[96:111]
	ds_read_b128 v[220:223], v188 offset:10816
	s_waitcnt lgkmcnt(7)
	v_mfma_f32_32x32x16_bf16 v[96:111], v[224:227], v[128:131], v[96:111]
	ds_read_b128 v[224:227], v188 offset:10848
	s_waitcnt lgkmcnt(7)
	v_mfma_f32_32x32x16_bf16 v[96:111], v[2:5], v[124:127], v[96:111]
	ds_read_b128 v[2:5], v188 offset:10880
	s_waitcnt lgkmcnt(7)
	v_mfma_f32_32x32x16_bf16 v[96:111], v[6:9], v[120:123], v[96:111]
	ds_read_b128 v[6:9], v188 offset:10912
	s_waitcnt lgkmcnt(7)
	v_mfma_f32_32x32x16_bf16 v[96:111], v[196:199], v[116:119], v[96:111]
	ds_read_b128 v[196:199], v188 offset:10944
	s_waitcnt lgkmcnt(7)
	v_mfma_f32_32x32x16_bf16 v[96:111], v[202:205], v[112:115], v[96:111]
	ds_read_b128 v[202:205], v188 offset:10976
	s_waitcnt lgkmcnt(7)
	v_mfma_f32_32x32x16_bf16 v[80:95], v[206:209], v[148:151], 0
	ds_read_b128 v[206:209], v188 offset:11008
	s_waitcnt lgkmcnt(7)
	v_mfma_f32_32x32x16_bf16 v[80:95], v[210:213], v[144:147], v[80:95]
	ds_read_b128 v[210:213], v188 offset:11040
	s_waitcnt lgkmcnt(7)
	v_mfma_f32_32x32x16_bf16 v[80:95], v[220:223], v[140:143], v[80:95]
	s_waitcnt lgkmcnt(6)
	v_mfma_f32_32x32x16_bf16 v[80:95], v[224:227], v[136:139], v[80:95]
	s_waitcnt lgkmcnt(5)
	v_mfma_f32_32x32x16_bf16 v[80:95], v[2:5], v[132:135], v[80:95]
	s_waitcnt lgkmcnt(4)
	v_mfma_f32_32x32x16_bf16 v[80:95], v[6:9], v[128:131], v[80:95]
	s_waitcnt lgkmcnt(3)
	v_mfma_f32_32x32x16_bf16 v[80:95], v[196:199], v[124:127], v[80:95]
	v_max_f32_e32 v0, v97, v97
	v_max_f32_e32 v10, v96, v96
	v_max_f32_e32 v0, v10, v0
	v_max3_f32 v0, v0, v98, v99
	v_max3_f32 v0, v0, v100, v101
	v_max3_f32 v0, v0, v102, v103
	v_max3_f32 v0, v0, v104, v105
	v_max3_f32 v0, v0, v106, v107
	v_max3_f32 v0, v0, v108, v109
	v_max3_f32 v0, v0, v110, v111
	v_and_b32_e32 v3, 64, v218
	v_xor_b32_e32 v2, 32, v218
	v_add_u32_e32 v3, 64, v3
	v_cmp_lt_i32_e64 s[12:13], v2, v3
	s_nop 1
	v_cndmask_b32_e64 v2, v218, v2, s[12:13]
	s_waitcnt lgkmcnt(2)
	v_mfma_f32_32x32x16_bf16 v[80:95], v[202:205], v[120:123], v[80:95]
	s_waitcnt lgkmcnt(1)
	v_mfma_f32_32x32x16_bf16 v[80:95], v[206:209], v[116:119], v[80:95]
	s_waitcnt lgkmcnt(0)
	v_mfma_f32_32x32x16_bf16 v[80:95], v[210:213], v[112:115], v[80:95]
	v_lshlrev_b32_e32 v2, 2, v2
	v_add_u32_e32 v224, 0x5000, v194
	v_add_u32_e32 v225, 0x6000, v194
	v_add_u32_e32 v226, 0x7000, v194
	v_add_u32_e32 v227, 0x8000, v194
	s_nop 6
	v_max3_f32 v0, v0, v80, v81
	v_max3_f32 v0, v0, v82, v83
	v_max3_f32 v0, v0, v84, v85
	v_max3_f32 v0, v0, v86, v87
	v_max3_f32 v0, v0, v88, v89
	v_max3_f32 v0, v0, v90, v91
	v_max3_f32 v0, v0, v92, v93
	v_max3_f32 v0, v0, v94, v95
	v_mov_b32_e32 v2, v0
	s_nop 1
	v_permlane32_swap_b32_e32 v2, v0
	s_nop 1
	ds_read2_b64 v[196:199], v224 offset0:128 offset1:130
	ds_read2_b64 v[202:205], v225 offset0:160 offset1:162
	ds_read2_b64 v[206:209], v226 offset0:192 offset1:194
	ds_read2_b64 v[210:213], v227 offset0:224 offset1:226
	ds_read2_b64 v[220:223], v224 offset0:132 offset1:134
	v_max3_f32 v0, v195, v0, v2
	v_sub_f32 v4, v97, v0
	v_sub_f32 v3, v96, v0
	v_sub_f32 v5, v100, v0
	v_sub_f32_e32 v2, v195, v0
	v_exp_f32_e32 v8, v4
	v_sub_f32 v4, v98, v0
	v_exp_f32_e32 v3, v3
	v_exp_f32_e32 v9, v4
	v_sub_f32 v4, v99, v0
	v_exp_f32_e32 v11, v5
	v_exp_f32_e32 v10, v4
	v_add_f32 v4, v1, v3
	v_sub_f32 v5, v101, v0
	v_exp_f32_e32 v2, v2
	v_add_f32 v4, v4, v8
	v_exp_f32_e32 v12, v5
	v_add_f32 v4, v4, v9
	v_sub_f32 v5, v102, v0
	v_cvt_pk_bf16_f32 v8, v3, v8
	v_add_f32 v4, v4, v10
	v_exp_f32_e32 v13, v5
	v_add_f32 v4, v4, v11
	v_sub_f32 v5, v103, v0
	v_add_f32 v4, v4, v12
	v_exp_f32_e32 v14, v5
	v_add_f32 v4, v4, v13
	v_cvt_pk_bf16_f32 v9, v9, v10
	v_add_f32 v96, v4, v14
	v_sub_f32 v4, v104, v0
	v_exp_f32_e32 v97, v4
	v_sub_f32 v4, v105, v0
	v_cvt_pk_bf16_f32 v10, v11, v12
	v_exp_f32_e32 v98, v4
	v_sub_f32 v4, v106, v0
	v_cvt_pk_bf16_f32 v11, v13, v14
	v_exp_f32_e32 v99, v4
	v_sub_f32 v4, v107, v0
	v_exp_f32_e32 v100, v4
	v_sub_f32 v4, v108, v0
	v_pk_mul_f32 v[64:65], v[64:65], v[2:3] op_sel_hi:[1,0]
	v_pk_mul_f32 v[66:67], v[66:67], v[2:3] op_sel_hi:[1,0]
	v_pk_mul_f32 v[68:69], v[68:69], v[2:3] op_sel_hi:[1,0]
	s_nop 0
	v_exp_f32_e32 v101, v4
	v_sub_f32 v4, v109, v0
	v_pk_mul_f32 v[70:71], v[70:71], v[2:3] op_sel_hi:[1,0]
	v_pk_mul_f32 v[72:73], v[72:73], v[2:3] op_sel_hi:[1,0]
	s_nop 0
	v_exp_f32_e32 v102, v4
	v_sub_f32 v4, v110, v0
	v_pk_mul_f32 v[74:75], v[74:75], v[2:3] op_sel_hi:[1,0]
	v_pk_mul_f32 v[76:77], v[76:77], v[2:3] op_sel_hi:[1,0]
	v_pk_mul_f32 v[78:79], v[78:79], v[2:3] op_sel_hi:[1,0]
	s_nop 0
	v_exp_f32_e32 v103, v4
	s_waitcnt lgkmcnt(4)
	v_mfma_f32_32x32x16_bf16 v[64:79], v[196:199], v[8:11], v[64:79]
	ds_read2_b64 v[196:199], v225 offset0:164 offset1:166
	v_pk_mul_f32 v[48:49], v[48:49], v[2:3] op_sel_hi:[1,0]
	v_pk_mul_f32 v[50:51], v[50:51], v[2:3] op_sel_hi:[1,0]
	v_pk_mul_f32 v[52:53], v[52:53], v[2:3] op_sel_hi:[1,0]
	v_pk_mul_f32 v[54:55], v[54:55], v[2:3] op_sel_hi:[1,0]
	v_pk_mul_f32 v[56:57], v[56:57], v[2:3] op_sel_hi:[1,0]
	v_pk_mul_f32 v[58:59], v[58:59], v[2:3] op_sel_hi:[1,0]
	v_pk_mul_f32 v[60:61], v[60:61], v[2:3] op_sel_hi:[1,0]
	v_pk_mul_f32 v[62:63], v[62:63], v[2:3] op_sel_hi:[1,0]
	s_waitcnt lgkmcnt(4)
	v_mfma_f32_32x32x16_bf16 v[48:63], v[202:205], v[8:11], v[48:63]
	ds_read2_b64 v[202:205], v226 offset0:196 offset1:198
	v_pk_mul_f32 v[32:33], v[32:33], v[2:3] op_sel_hi:[1,0]
	v_pk_mul_f32 v[34:35], v[34:35], v[2:3] op_sel_hi:[1,0]
	v_pk_mul_f32 v[36:37], v[36:37], v[2:3] op_sel_hi:[1,0]
	v_pk_mul_f32 v[38:39], v[38:39], v[2:3] op_sel_hi:[1,0]
	v_pk_mul_f32 v[40:41], v[40:41], v[2:3] op_sel_hi:[1,0]
	v_pk_mul_f32 v[42:43], v[42:43], v[2:3] op_sel_hi:[1,0]
	v_pk_mul_f32 v[44:45], v[44:45], v[2:3] op_sel_hi:[1,0]
	v_pk_mul_f32 v[46:47], v[46:47], v[2:3] op_sel_hi:[1,0]
	v_pk_mul_f32 v[16:17], v[16:17], v[2:3] op_sel_hi:[1,0]
	v_pk_mul_f32 v[18:19], v[18:19], v[2:3] op_sel_hi:[1,0]
	v_pk_mul_f32 v[20:21], v[20:21], v[2:3] op_sel_hi:[1,0]
	s_waitcnt lgkmcnt(4)
	v_mfma_f32_32x32x16_bf16 v[32:47], v[206:209], v[8:11], v[32:47]
	ds_read2_b64 v[206:209], v227 offset0:228 offset1:230
	v_pk_mul_f32 v[22:23], v[22:23], v[2:3] op_sel_hi:[1,0]
	v_pk_mul_f32 v[24:25], v[24:25], v[2:3] op_sel_hi:[1,0]
	v_pk_mul_f32 v[26:27], v[26:27], v[2:3] op_sel_hi:[1,0]
	v_pk_mul_f32 v[28:29], v[28:29], v[2:3] op_sel_hi:[1,0]
	v_pk_mul_f32 v[30:31], v[30:31], v[2:3] op_sel_hi:[1,0]
	v_mov_b32_e32 v195, v0
	s_waitcnt lgkmcnt(4)
	v_mfma_f32_32x32x16_bf16 v[16:31], v[210:213], v[8:11], v[16:31]
	ds_read2_b64 v[210:213], v224 offset0:136 offset1:138
	v_sub_f32 v8, v111, v0
	v_cvt_pk_bf16_f32 v9, v99, v100
	v_exp_f32_e32 v107, v8
	v_cvt_pk_bf16_f32 v8, v97, v98
	v_cvt_pk_bf16_f32 v10, v101, v102
	v_cvt_pk_bf16_f32 v11, v103, v107
	s_nop 0
	s_waitcnt lgkmcnt(4)
	v_mfma_f32_32x32x16_bf16 v[64:79], v[220:223], v[8:11], v[64:79]
	ds_read2_b64 v[220:223], v225 offset0:168 offset1:170
	v_add_f32 v4, v96, v97
	s_nop 0
	v_add_f32 v4, v4, v98
	s_nop 0
	v_add_f32 v4, v4, v99
	s_nop 0
	v_add_f32 v96, v4, v100
	v_sub_f32 v4, v80, v0
	s_waitcnt lgkmcnt(4)
	v_mfma_f32_32x32x16_bf16 v[48:63], v[196:199], v[8:11], v[48:63]
	ds_read2_b64 v[196:199], v226 offset0:200 offset1:202
	v_exp_f32_e32 v80, v4
	v_sub_f32 v12, v81, v0
	s_nop 0
	v_exp_f32_e32 v81, v12
	v_sub_f32 v12, v82, v0
	s_nop 0
	v_exp_f32_e32 v82, v12
	v_sub_f32 v12, v83, v0
	s_waitcnt lgkmcnt(4)
	v_mfma_f32_32x32x16_bf16 v[32:47], v[202:205], v[8:11], v[32:47]
	ds_read2_b64 v[202:205], v227 offset0:232 offset1:234
	v_exp_f32_e32 v83, v12
	v_sub_f32 v4, v84, v0
	s_nop 0
	v_exp_f32_e32 v84, v4
	v_sub_f32 v4, v85, v0
	s_nop 0
	v_exp_f32_e32 v85, v4
	v_sub_f32 v4, v86, v0
	s_waitcnt lgkmcnt(4)
	v_mfma_f32_32x32x16_bf16 v[16:31], v[206:209], v[8:11], v[16:31]
	ds_read2_b64 v[206:209], v224 offset0:140 offset1:142
	v_exp_f32_e32 v86, v4
	v_sub_f32 v8, v87, v0
	v_exp_f32_e32 v87, v8
	v_cvt_pk_bf16_f32 v8, v80, v81
	v_cvt_pk_bf16_f32 v9, v82, v83
	v_cvt_pk_bf16_f32 v10, v84, v85
	v_cvt_pk_bf16_f32 v11, v86, v87
	s_nop 0
	s_waitcnt lgkmcnt(4)
	v_mfma_f32_32x32x16_bf16 v[64:79], v[210:213], v[8:11], v[64:79]
	ds_read2_b64 v[210:213], v225 offset0:172 offset1:174
	v_add_f32 v4, v96, v101
	s_nop 0
	v_add_f32 v4, v4, v102
	s_nop 0
	v_add_f32 v4, v4, v103
	s_nop 0
	v_add_f32 v96, v4, v107
	v_sub_f32 v4, v88, v0
	s_waitcnt lgkmcnt(4)
	v_mfma_f32_32x32x16_bf16 v[48:63], v[220:223], v[8:11], v[48:63]
	ds_read2_b64 v[220:223], v226 offset0:204 offset1:206
	v_exp_f32_e32 v88, v4
	v_sub_f32 v12, v89, v0
	s_nop 0
	v_exp_f32_e32 v89, v12
	v_sub_f32 v12, v90, v0
	s_nop 0
	v_exp_f32_e32 v90, v12
	v_sub_f32 v12, v91, v0
	s_waitcnt lgkmcnt(4)
	v_mfma_f32_32x32x16_bf16 v[32:47], v[196:199], v[8:11], v[32:47]
	ds_read2_b64 v[196:199], v227 offset0:236 offset1:238
	v_exp_f32_e32 v91, v12
	v_sub_f32 v4, v92, v0
	s_nop 0
	v_exp_f32_e32 v92, v4
	v_sub_f32 v4, v93, v0
	s_nop 0
	v_exp_f32_e32 v93, v4
	v_sub_f32 v4, v94, v0
	s_waitcnt lgkmcnt(4)
	v_mfma_f32_32x32x16_bf16 v[16:31], v[202:205], v[8:11], v[16:31]
	v_exp_f32_e32 v94, v4
	v_sub_f32 v8, v95, v0
	v_cvt_pk_bf16_f32 v9, v90, v91
	v_exp_f32_e32 v95, v8
	v_cvt_pk_bf16_f32 v8, v88, v89
	v_cvt_pk_bf16_f32 v10, v92, v93
	v_add_f32 v3, v96, v80
	v_cvt_pk_bf16_f32 v11, v94, v95
	v_add_f32 v3, v3, v81
	s_nop 0
	v_add_f32 v3, v3, v82
	s_waitcnt lgkmcnt(3)
	v_mfma_f32_32x32x16_bf16 v[64:79], v[206:209], v[8:11], v[64:79]
	v_add_f32 v3, v3, v83
	s_nop 0
	v_add_f32 v3, v3, v84
	s_nop 0
	v_add_f32 v3, v3, v85
	s_waitcnt lgkmcnt(2)
	v_mfma_f32_32x32x16_bf16 v[48:63], v[210:213], v[8:11], v[48:63]
	v_add_f32 v3, v3, v86
	s_nop 0
	v_add_f32 v3, v3, v87
	s_nop 0
	v_add_f32 v3, v3, v88
	s_nop 0
	v_add_f32 v3, v3, v89
	s_waitcnt lgkmcnt(1)
	v_mfma_f32_32x32x16_bf16 v[32:47], v[220:223], v[8:11], v[32:47]
	v_add_f32 v3, v3, v90
	s_nop 0
	v_add_f32 v3, v3, v91
	s_nop 0
	v_add_f32 v3, v3, v92
	s_nop 0
	v_add_f32 v3, v3, v93
	s_waitcnt lgkmcnt(0)
	v_mfma_f32_32x32x16_bf16 v[16:31], v[196:199], v[8:11], v[16:31]
	v_add_f32 v3, v3, v94
	s_nop 0
	v_add_f32 v3, v3, v95
	s_nop 0
	v_fmac_f32_e32 v3, v184, v2
	v_mov_b32_e32 v184, v3
	s_branch .LBB0_555

.LBB0_598:
	s_and_saveexec_b64 s[24:25], s[6:7]
	s_cbranch_execz .LBB0_587
	ds_read_b128 v[194:197], v185
	ds_read_b128 v[202:205], v185 offset:32
	ds_read_b128 v[206:209], v185 offset:64
	ds_read_b128 v[210:213], v185 offset:96
	ds_read_b128 v[220:223], v185 offset:128
	ds_read_b128 v[224:227], v185 offset:160
	ds_read_b128 v[2:5], v185 offset:192
	ds_read_b128 v[6:9], v185 offset:224
	s_waitcnt lgkmcnt(7)
	v_mfma_f32_32x32x16_bf16 v[96:111], v[194:197], v[148:151], 0
	ds_read_b128 v[194:197], v185 offset:256
	s_waitcnt lgkmcnt(7)
	v_mfma_f32_32x32x16_bf16 v[96:111], v[202:205], v[144:147], v[96:111]
	ds_read_b128 v[202:205], v185 offset:288
	s_waitcnt lgkmcnt(7)
	v_mfma_f32_32x32x16_bf16 v[96:111], v[206:209], v[140:143], v[96:111]
	ds_read_b128 v[206:209], v185 offset:10752
	s_waitcnt lgkmcnt(7)
	v_mfma_f32_32x32x16_bf16 v[96:111], v[210:213], v[136:139], v[96:111]
	ds_read_b128 v[210:213], v185 offset:10784
	s_waitcnt lgkmcnt(7)
	v_mfma_f32_32x32x16_bf16 v[96:111], v[220:223], v[132:135], v[96:111]
	ds_read_b128 v[220:223], v185 offset:10816
	s_waitcnt lgkmcnt(7)
	v_mfma_f32_32x32x16_bf16 v[96:111], v[224:227], v[128:131], v[96:111]
	ds_read_b128 v[224:227], v185 offset:10848
	s_waitcnt lgkmcnt(7)
	v_mfma_f32_32x32x16_bf16 v[96:111], v[2:5], v[124:127], v[96:111]
	ds_read_b128 v[2:5], v185 offset:10880
	s_waitcnt lgkmcnt(7)
	v_mfma_f32_32x32x16_bf16 v[96:111], v[6:9], v[120:123], v[96:111]
	ds_read_b128 v[6:9], v185 offset:10912
	s_waitcnt lgkmcnt(7)
	v_mfma_f32_32x32x16_bf16 v[96:111], v[194:197], v[116:119], v[96:111]
	ds_read_b128 v[194:197], v185 offset:10944
	s_waitcnt lgkmcnt(7)
	v_mfma_f32_32x32x16_bf16 v[96:111], v[202:205], v[112:115], v[96:111]
	ds_read_b128 v[202:205], v185 offset:10976
	s_waitcnt lgkmcnt(7)
	v_mfma_f32_32x32x16_bf16 v[80:95], v[206:209], v[148:151], 0
	ds_read_b128 v[206:209], v185 offset:11008
	s_waitcnt lgkmcnt(7)
	v_mfma_f32_32x32x16_bf16 v[80:95], v[210:213], v[144:147], v[80:95]
	ds_read_b128 v[210:213], v185 offset:11040
	s_waitcnt lgkmcnt(7)
	v_mfma_f32_32x32x16_bf16 v[80:95], v[220:223], v[140:143], v[80:95]
	s_waitcnt lgkmcnt(6)
	v_mfma_f32_32x32x16_bf16 v[80:95], v[224:227], v[136:139], v[80:95]
	s_waitcnt lgkmcnt(5)
	v_mfma_f32_32x32x16_bf16 v[80:95], v[2:5], v[132:135], v[80:95]
	s_waitcnt lgkmcnt(4)
	v_mfma_f32_32x32x16_bf16 v[80:95], v[6:9], v[128:131], v[80:95]
	s_waitcnt lgkmcnt(3)
	v_mfma_f32_32x32x16_bf16 v[80:95], v[194:197], v[124:127], v[80:95]
	v_max_f32_e32 v0, v97, v97
	v_max_f32_e32 v10, v96, v96
	v_max_f32_e32 v0, v10, v0
	v_max3_f32 v0, v0, v98, v99
	v_max3_f32 v0, v0, v100, v101
	v_max3_f32 v0, v0, v102, v103
	v_max3_f32 v0, v0, v104, v105
	v_max3_f32 v0, v0, v106, v107
	v_max3_f32 v0, v0, v108, v109
	v_max3_f32 v0, v0, v110, v111
	v_and_b32_e32 v3, 64, v218
	v_xor_b32_e32 v2, 32, v218
	v_add_u32_e32 v3, 64, v3
	v_cmp_lt_i32_e32 vcc, v2, v3
	s_nop 1
	v_cndmask_b32_e32 v2, v218, v2, vcc
	s_waitcnt lgkmcnt(2)
	v_mfma_f32_32x32x16_bf16 v[80:95], v[202:205], v[120:123], v[80:95]
	s_waitcnt lgkmcnt(1)
	v_mfma_f32_32x32x16_bf16 v[80:95], v[206:209], v[116:119], v[80:95]
	s_waitcnt lgkmcnt(0)
	v_mfma_f32_32x32x16_bf16 v[80:95], v[210:213], v[112:115], v[80:95]
	v_lshlrev_b32_e32 v2, 2, v2
	v_add_u32_e32 v224, 0x5000, v191
	v_add_u32_e32 v225, 0x6000, v191
	v_add_u32_e32 v226, 0x7000, v191
	v_add_u32_e32 v227, 0x8000, v191
	s_nop 6
	v_max3_f32 v0, v0, v80, v81
	v_max3_f32 v0, v0, v82, v83
	v_max3_f32 v0, v0, v84, v85
	v_max3_f32 v0, v0, v86, v87
	v_max3_f32 v0, v0, v88, v89
	v_max3_f32 v0, v0, v90, v91
	v_max3_f32 v0, v0, v92, v93
	v_max3_f32 v0, v0, v94, v95
	v_mov_b32_e32 v2, v0
	s_nop 1
	v_permlane32_swap_b32_e32 v2, v0
	s_nop 1
	ds_read2_b64 v[194:197], v224 offset0:128 offset1:130
	ds_read2_b64 v[202:205], v225 offset0:160 offset1:162
	ds_read2_b64 v[206:209], v226 offset0:192 offset1:194
	ds_read2_b64 v[210:213], v227 offset0:224 offset1:226
	ds_read2_b64 v[220:223], v224 offset0:132 offset1:134
	v_max3_f32 v0, v192, v0, v2
	v_sub_f32 v4, v97, v0
	v_sub_f32 v3, v96, v0
	v_sub_f32 v5, v100, v0
	v_sub_f32_e32 v2, v192, v0
	v_exp_f32_e32 v8, v4
	v_sub_f32 v4, v98, v0
	v_exp_f32_e32 v3, v3
	v_exp_f32_e32 v9, v4
	v_sub_f32 v4, v99, v0
	v_exp_f32_e32 v11, v5
	v_exp_f32_e32 v10, v4
	v_add_f32 v4, v1, v3
	v_sub_f32 v5, v101, v0
	v_exp_f32_e32 v2, v2
	v_add_f32 v4, v4, v8
	v_exp_f32_e32 v12, v5
	v_add_f32 v4, v4, v9
	v_sub_f32 v5, v102, v0
	v_cvt_pk_bf16_f32 v8, v3, v8
	v_add_f32 v4, v4, v10
	v_exp_f32_e32 v13, v5
	v_add_f32 v4, v4, v11
	v_sub_f32 v5, v103, v0
	v_add_f32 v4, v4, v12
	v_exp_f32_e32 v14, v5
	v_add_f32 v4, v4, v13
	v_cvt_pk_bf16_f32 v9, v9, v10
	v_add_f32 v96, v4, v14
	v_sub_f32 v4, v104, v0
	v_exp_f32_e32 v97, v4
	v_sub_f32 v4, v105, v0
	v_cvt_pk_bf16_f32 v10, v11, v12
	v_exp_f32_e32 v98, v4
	v_sub_f32 v4, v106, v0
	v_cvt_pk_bf16_f32 v11, v13, v14
	v_exp_f32_e32 v99, v4
	v_sub_f32 v4, v107, v0
	v_exp_f32_e32 v100, v4
	v_sub_f32 v4, v108, v0
	v_pk_mul_f32 v[64:65], v[64:65], v[2:3] op_sel_hi:[1,0]
	v_pk_mul_f32 v[66:67], v[66:67], v[2:3] op_sel_hi:[1,0]
	v_pk_mul_f32 v[68:69], v[68:69], v[2:3] op_sel_hi:[1,0]
	s_nop 0
	v_exp_f32_e32 v101, v4
	v_sub_f32 v4, v109, v0
	v_pk_mul_f32 v[70:71], v[70:71], v[2:3] op_sel_hi:[1,0]
	v_pk_mul_f32 v[72:73], v[72:73], v[2:3] op_sel_hi:[1,0]
	s_nop 0
	v_exp_f32_e32 v102, v4
	v_sub_f32 v4, v110, v0
	v_pk_mul_f32 v[74:75], v[74:75], v[2:3] op_sel_hi:[1,0]
	v_pk_mul_f32 v[76:77], v[76:77], v[2:3] op_sel_hi:[1,0]
	v_pk_mul_f32 v[78:79], v[78:79], v[2:3] op_sel_hi:[1,0]
	s_nop 0
	v_exp_f32_e32 v103, v4
	s_waitcnt lgkmcnt(4)
	v_mfma_f32_32x32x16_bf16 v[64:79], v[194:197], v[8:11], v[64:79]
	ds_read2_b64 v[194:197], v225 offset0:164 offset1:166
	v_pk_mul_f32 v[48:49], v[48:49], v[2:3] op_sel_hi:[1,0]
	v_pk_mul_f32 v[50:51], v[50:51], v[2:3] op_sel_hi:[1,0]
	v_pk_mul_f32 v[52:53], v[52:53], v[2:3] op_sel_hi:[1,0]
	v_pk_mul_f32 v[54:55], v[54:55], v[2:3] op_sel_hi:[1,0]
	v_pk_mul_f32 v[56:57], v[56:57], v[2:3] op_sel_hi:[1,0]
	v_pk_mul_f32 v[58:59], v[58:59], v[2:3] op_sel_hi:[1,0]
	v_pk_mul_f32 v[60:61], v[60:61], v[2:3] op_sel_hi:[1,0]
	v_pk_mul_f32 v[62:63], v[62:63], v[2:3] op_sel_hi:[1,0]
	s_waitcnt lgkmcnt(4)
	v_mfma_f32_32x32x16_bf16 v[48:63], v[202:205], v[8:11], v[48:63]
	ds_read2_b64 v[202:205], v226 offset0:196 offset1:198
	v_pk_mul_f32 v[32:33], v[32:33], v[2:3] op_sel_hi:[1,0]
	v_pk_mul_f32 v[34:35], v[34:35], v[2:3] op_sel_hi:[1,0]
	v_pk_mul_f32 v[36:37], v[36:37], v[2:3] op_sel_hi:[1,0]
	v_pk_mul_f32 v[38:39], v[38:39], v[2:3] op_sel_hi:[1,0]
	v_pk_mul_f32 v[40:41], v[40:41], v[2:3] op_sel_hi:[1,0]
	v_pk_mul_f32 v[42:43], v[42:43], v[2:3] op_sel_hi:[1,0]
	v_pk_mul_f32 v[44:45], v[44:45], v[2:3] op_sel_hi:[1,0]
	v_pk_mul_f32 v[46:47], v[46:47], v[2:3] op_sel_hi:[1,0]
	v_pk_mul_f32 v[16:17], v[16:17], v[2:3] op_sel_hi:[1,0]
	v_pk_mul_f32 v[18:19], v[18:19], v[2:3] op_sel_hi:[1,0]
	v_pk_mul_f32 v[20:21], v[20:21], v[2:3] op_sel_hi:[1,0]
	s_waitcnt lgkmcnt(4)
	v_mfma_f32_32x32x16_bf16 v[32:47], v[206:209], v[8:11], v[32:47]
	ds_read2_b64 v[206:209], v227 offset0:228 offset1:230
	v_pk_mul_f32 v[22:23], v[22:23], v[2:3] op_sel_hi:[1,0]
	v_pk_mul_f32 v[24:25], v[24:25], v[2:3] op_sel_hi:[1,0]
	v_pk_mul_f32 v[26:27], v[26:27], v[2:3] op_sel_hi:[1,0]
	v_pk_mul_f32 v[28:29], v[28:29], v[2:3] op_sel_hi:[1,0]
	v_pk_mul_f32 v[30:31], v[30:31], v[2:3] op_sel_hi:[1,0]
	v_mov_b32_e32 v192, v0
	s_waitcnt lgkmcnt(4)
	v_mfma_f32_32x32x16_bf16 v[16:31], v[210:213], v[8:11], v[16:31]
	ds_read2_b64 v[210:213], v224 offset0:136 offset1:138
	v_sub_f32 v8, v111, v0
	v_cvt_pk_bf16_f32 v9, v99, v100
	v_exp_f32_e32 v107, v8
	v_cvt_pk_bf16_f32 v8, v97, v98
	v_cvt_pk_bf16_f32 v10, v101, v102
	v_cvt_pk_bf16_f32 v11, v103, v107
	s_nop 0
	s_waitcnt lgkmcnt(4)
	v_mfma_f32_32x32x16_bf16 v[64:79], v[220:223], v[8:11], v[64:79]
	ds_read2_b64 v[220:223], v225 offset0:168 offset1:170
	v_add_f32 v4, v96, v97
	s_nop 0
	v_add_f32 v4, v4, v98
	s_nop 0
	v_add_f32 v4, v4, v99
	s_nop 0
	v_add_f32 v96, v4, v100
	v_sub_f32 v4, v80, v0
	s_waitcnt lgkmcnt(4)
	v_mfma_f32_32x32x16_bf16 v[48:63], v[194:197], v[8:11], v[48:63]
	ds_read2_b64 v[194:197], v226 offset0:200 offset1:202
	v_exp_f32_e32 v80, v4
	v_sub_f32 v12, v81, v0
	s_nop 0
	v_exp_f32_e32 v81, v12
	v_sub_f32 v12, v82, v0
	s_nop 0
	v_exp_f32_e32 v82, v12
	v_sub_f32 v12, v83, v0
	s_waitcnt lgkmcnt(4)
	v_mfma_f32_32x32x16_bf16 v[32:47], v[202:205], v[8:11], v[32:47]
	ds_read2_b64 v[202:205], v227 offset0:232 offset1:234
	v_exp_f32_e32 v83, v12
	v_sub_f32 v4, v84, v0
	s_nop 0
	v_exp_f32_e32 v84, v4
	v_sub_f32 v4, v85, v0
	s_nop 0
	v_exp_f32_e32 v85, v4
	v_sub_f32 v4, v86, v0
	s_waitcnt lgkmcnt(4)
	v_mfma_f32_32x32x16_bf16 v[16:31], v[206:209], v[8:11], v[16:31]
	ds_read2_b64 v[206:209], v224 offset0:140 offset1:142
	v_exp_f32_e32 v86, v4
	v_sub_f32 v8, v87, v0
	v_exp_f32_e32 v87, v8
	v_cvt_pk_bf16_f32 v8, v80, v81
	v_cvt_pk_bf16_f32 v9, v82, v83
	v_cvt_pk_bf16_f32 v10, v84, v85
	v_cvt_pk_bf16_f32 v11, v86, v87
	s_nop 0
	s_waitcnt lgkmcnt(4)
	v_mfma_f32_32x32x16_bf16 v[64:79], v[210:213], v[8:11], v[64:79]
	ds_read2_b64 v[210:213], v225 offset0:172 offset1:174
	v_add_f32 v4, v96, v101
	s_nop 0
	v_add_f32 v4, v4, v102
	s_nop 0
	v_add_f32 v4, v4, v103
	s_nop 0
	v_add_f32 v96, v4, v107
	v_sub_f32 v4, v88, v0
	s_waitcnt lgkmcnt(4)
	v_mfma_f32_32x32x16_bf16 v[48:63], v[220:223], v[8:11], v[48:63]
	ds_read2_b64 v[220:223], v226 offset0:204 offset1:206
	v_exp_f32_e32 v88, v4
	v_sub_f32 v12, v89, v0
	s_nop 0
	v_exp_f32_e32 v89, v12
	v_sub_f32 v12, v90, v0
	s_nop 0
	v_exp_f32_e32 v90, v12
	v_sub_f32 v12, v91, v0
	s_waitcnt lgkmcnt(4)
	v_mfma_f32_32x32x16_bf16 v[32:47], v[194:197], v[8:11], v[32:47]
	ds_read2_b64 v[194:197], v227 offset0:236 offset1:238
	v_exp_f32_e32 v91, v12
	v_sub_f32 v4, v92, v0
	s_nop 0
	v_exp_f32_e32 v92, v4
	v_sub_f32 v4, v93, v0
	s_nop 0
	v_exp_f32_e32 v93, v4
	v_sub_f32 v4, v94, v0
	s_waitcnt lgkmcnt(4)
	v_mfma_f32_32x32x16_bf16 v[16:31], v[202:205], v[8:11], v[16:31]
	v_exp_f32_e32 v94, v4
	v_sub_f32 v8, v95, v0
	v_cvt_pk_bf16_f32 v9, v90, v91
	v_exp_f32_e32 v95, v8
	v_cvt_pk_bf16_f32 v8, v88, v89
	v_cvt_pk_bf16_f32 v10, v92, v93
	v_add_f32 v3, v96, v80
	v_cvt_pk_bf16_f32 v11, v94, v95
	v_add_f32 v3, v3, v81
	s_nop 0
	v_add_f32 v3, v3, v82
	s_waitcnt lgkmcnt(3)
	v_mfma_f32_32x32x16_bf16 v[64:79], v[206:209], v[8:11], v[64:79]
	v_add_f32 v3, v3, v83
	s_nop 0
	v_add_f32 v3, v3, v84
	s_nop 0
	v_add_f32 v3, v3, v85
	s_waitcnt lgkmcnt(2)
	v_mfma_f32_32x32x16_bf16 v[48:63], v[210:213], v[8:11], v[48:63]
	v_add_f32 v3, v3, v86
	s_nop 0
	v_add_f32 v3, v3, v87
	s_nop 0
	v_add_f32 v3, v3, v88
	s_nop 0
	v_add_f32 v3, v3, v89
	s_waitcnt lgkmcnt(1)
	v_mfma_f32_32x32x16_bf16 v[32:47], v[220:223], v[8:11], v[32:47]
	v_add_f32 v3, v3, v90
	s_nop 0
	v_add_f32 v3, v3, v91
	s_nop 0
	v_add_f32 v3, v3, v92
	s_nop 0
	v_add_f32 v3, v3, v93
	s_waitcnt lgkmcnt(0)
	v_mfma_f32_32x32x16_bf16 v[16:31], v[194:197], v[8:11], v[16:31]
	v_add_f32 v3, v3, v94
	s_nop 0
	v_add_f32 v3, v3, v95
	s_nop 0
	v_fmac_f32_e32 v3, v184, v2
	v_mov_b32_e32 v184, v3
	s_branch .LBB0_587
